# MLA attention unit start: first two K/V tile LDS-DMAs issued right after the Q loads instead of after waiting for Q
# baseline (speedup 1.0000x reference)
; #define AT_DMA(t_, slot_) do { _Pragma("unroll") for (int j = 0; j < NJ; ++j) { const int g = wid + 8 * j; if (g < NIT) { \
;         const bf16_t* src_ = (g < NKI) ? (Kp + (size_t)(t_) * 64 * ldk + goff[j]) : (VTp + (size_t)(t_) * 64 + goff[j]); \
;         __builtin_amdgcn_global_load_lds((const unsigned*)src_, (LAS unsigned*)(lds + (slot_) * BUF + g * 1024), 16, 0, 0); } } } while (0)
; #define AT_WAIT_KEEP1() do { if (full) asm volatile("s_waitcnt vmcnt(%0)" :: "n"(NJ) : "memory"); else asm volatile("s_waitcnt vmcnt(%0)" :: "n"(NJ - 1) : "memory"); } while (0)
; #define AT_WAIT_ALL() asm volatile("s_waitcnt vmcnt(0)" ::: "memory")
; template <int DQK, int QF>
; __device__ __forceinline__ void attn_unit_dma(LAS unsigned char* lds, const bf16_t* Qp, int ldq, const bf16_t* Kp, int ldk, const bf16_t* VTp, int ldvt, bf16_t* Op, int ldo, int nkt, int wave_last, const float* qgam, float qscale) {
;     ...
;     const int tid = threadIdx.x, wid = __builtin_amdgcn_readfirstlane(tid >> 6), lane = tid & 63, fr = lane & 15, fq = lane >> 4;
;     bf16x8 qreg[QF][KS];
; #pragma unroll
;     for (int qf = 0; qf < QF; ++qf)
; #pragma unroll
;         for (int s = 0; s < KS; ++s) qreg[qf][s] = *(const bf16x8*)(Qp + (size_t)(16 * QF * wid + 16 * qf + fr) * ldq + s * 32 + fq * 8);
;     ...
;     constexpr int NKI = KBYTES / 1024, NVI = VBYTES / 1024, NIT = NKI + NVI, NJ = (NIT + 7) / 8, KCH = KROW / 16, VCH = VROW / 16;
;     static_assert(KBYTES % 1024 == 0 && VBYTES % 1024 == 0, "slot image is whole 1 KiB pieces");
;     int goff[NJ];
; #pragma unroll
;     for (int j = 0; j < NJ; ++j) {
;         const int g = wid + 8 * j;
;         if (g < NKI) { const int q = g * 64 + lane; int row = q / KCH, cc = q % KCH; if (cc == KCH - 1) cc = KCH - 2; goff[j] = row * ldk + cc * 8; }
;         else { const int q = (g - NKI) * 64 + lane; int row = q / VCH, cc = q % VCH; if (cc == VCH - 1) cc = VCH - 2; goff[j] = row * ldvt + cc * 8; }
;     }
;     const bool full = (wid + 8 * (NJ - 1)) < NIT;
;     ...
;     asm volatile("s_waitcnt vmcnt(0)" ::: "memory");
;     AT_DMA(0, 0);
;     if (nkt > 1) { AT_DMA(1, 1); AT_WAIT_KEEP1(); } else AT_WAIT_ALL();
.LBB0_1062:
	s_and_b64 s[12:13], s[42:43], exec
	s_cselect_b32 s0, s79, s81
	s_lshl_b32 s14, s0, 8
	s_ashr_i32 s12, s14, 31
	s_add_u32 s38, s24, s14
	v_readfirstlane_b32 s33, v185
	s_addc_u32 s39, s25, s12
	s_lshr_b32 s16, s33, 6
	v_lshl_or_b32 v188, s16, 5, v212
	s_mul_i32 s17, s39, 0xc00
	v_mad_u64_u32 v[24:25], s[12:13], s38, v187, v[194:195]
	v_add_u32_e32 v25, s17, v25
	v_or_b32_e32 v198, 16, v188
	v_mad_u64_u32 v[20:21], s[12:13], v188, s74, v[24:25]
	v_mad_u64_u32 v[44:45], s[12:13], v198, s74, v[24:25]
	global_load_dwordx4 v[0:3], v[20:21], off
	global_load_dwordx4 v[4:7], v[20:21], off offset:64
	global_load_dwordx4 v[8:11], v[20:21], off offset:128
	global_load_dwordx4 v[12:15], v[20:21], off offset:192
	global_load_dwordx4 v[16:19], v[20:21], off offset:256
	s_nop 0
	global_load_dwordx4 v[20:23], v[20:21], off offset:320
	s_nop 0
	global_load_dwordx4 v[24:27], v[44:45], off
	global_load_dwordx4 v[28:31], v[44:45], off offset:64
	global_load_dwordx4 v[32:35], v[44:45], off offset:128
	global_load_dwordx4 v[36:39], v[44:45], off offset:192
	global_load_dwordx4 v[40:43], v[44:45], off offset:256
	s_nop 0
	global_load_dwordx4 v[44:47], v[44:45], off offset:320
	v_lshrrev_b32_e32 v206, 2, v184
	v_and_b32_e32 v207, 3, v184
	v_lshrrev_b32_e32 v199, 4, v184
	v_and_b32_e32 v199, 2, v199
	v_xor_b32_e32 v207, v207, v199
	v_lshrrev_b32_e32 v199, 2, v206
	v_and_b32_e32 v208, 3, v206
	v_lshl_add_u32 v199, v199, 3, v208
	s_and_b32 s33, s16, 3
	s_lshr_b32 s84, s33, 1
	s_lshl_b32 s84, s84, 5
	s_and_b32 s33, s33, 1
	s_lshl_b32 s33, s33, 2
	s_add_i32 s33, s33, s84
	v_add_u32_e32 v199, s33, v199
	v_mul_u32_u24_e32 v199, 0xc00, v199
	v_lshl_add_u32 v199, v207, 4, v199
	s_lshr_b32 s33, s16, 2
	s_lshl_b32 s33, s33, 6
	v_add_u32_e32 v200, s33, v199
	s_lshl_b32 s33, s16, 4
	v_add_u32_e32 v199, s33, v206
	v_lshlrev_b32_e32 v199, 15, v199
	v_lshl_add_u32 v202, v207, 4, v199
	v_and_b32_e32 v206, 15, v184
	v_lshrrev_b32_e32 v207, 4, v184
	v_lshlrev_b32_e32 v204, 6, v206
	v_lshl_add_u32 v204, v207, 4, v204
	v_lshrrev_b32_e32 v206, 3, v206
	v_lshlrev_b32_e32 v206, 5, v206
	v_xor_b32_e32 v204, v204, v206
	s_lshl_b32 s33, s16, 10
	s_mov_b32 m0, s33
	s_nop 0
	global_load_lds_dwordx4 v200, s[82:83]
	s_add_i32 m0, s33, 0x1f80
	s_nop 0
	global_load_lds_dwordx4 v200, s[82:83] offset:128
	s_add_i32 m0, s33, 0x3f00
	s_nop 0
	global_load_lds_dwordx4 v200, s[82:83] offset:256
	s_add_i32 m0, s33, 0x6000
	s_nop 0
	global_load_lds_dwordx4 v202, s[26:27]
	s_add_i32 m0, s33, 0x7fc0
	s_nop 0
	global_load_lds_dwordx4 v202, s[26:27] offset:64
	s_add_i32 s33, s33, 0xa000
	s_mov_b32 m0, s33
	s_nop 0
	global_load_lds_dwordx4 v200, s[92:93]
	s_add_i32 m0, s33, 0x1f80
	s_nop 0
	global_load_lds_dwordx4 v200, s[92:93] offset:128
	s_add_i32 m0, s33, 0x3f00
	s_nop 0
	global_load_lds_dwordx4 v200, s[92:93] offset:256
	s_add_i32 m0, s33, 0x6000
	s_nop 0
	global_load_lds_dwordx4 v202, s[90:91]
	s_add_i32 m0, s33, 0x7fc0
	s_nop 0
	global_load_lds_dwordx4 v202, s[90:91] offset:64
	s_cmpk_lt_u32 s33, 0x640
	s_cselect_b64 s[44:45], -1, 0
	s_cmpk_gt_u32 s33, 0x63f
	s_mov_b64 s[12:13], -1
	s_cbranch_scc0 .LBB0_1064
	s_and_b32 s12, s33, 0xffffffc0
	v_add_u32_e32 v48, s12, v213
	v_mul_hi_u32 v49, v48, s75
	v_lshrrev_b32_e32 v49, 1, v49
	v_lshl_add_u32 v50, v49, 3, v49
	v_sub_u32_e32 v48, v48, v50
	v_lshlrev_b32_e32 v50, 3, v48
	v_cmp_ne_u32_e32 vcc, 8, v48
	s_mov_b64 s[12:13], 0
	s_nop 0
	v_cndmask_b32_e32 v48, 56, v50, vcc
	s_nop 0
.LBB0_1064:
	s_andn2_b64 vcc, exec, s[12:13]
	s_cbranch_vccnz .LBB0_1066
	s_and_b32 s12, s33, 0x7c0
	v_bitop3_b32 v49, s12, v219, v184 bitop3:0xc8
	v_or_b32_e32 v48, s12, v184
	v_mul_u32_u24_e32 v49, 0x47af, v49
	v_sub_u16_sdwa v50, v48, v49 dst_sel:DWORD dst_unused:UNUSED_PAD src0_sel:DWORD src1_sel:WORD_1
	v_lshrrev_b16_e32 v50, 1, v50
	v_add_u16_sdwa v49, v50, v49 dst_sel:DWORD dst_unused:UNUSED_PAD src0_sel:DWORD src1_sel:WORD_1
	v_lshrrev_b16_e32 v49, 4, v49
	v_mul_lo_u16_e32 v50, 25, v49
	v_sub_u16_e32 v48, v48, v50
	v_lshlrev_b16_e32 v50, 3, v48
	v_cmp_ne_u16_e32 vcc, 24, v48
	v_mul_u32_u24_e32 v49, 0x600, v49
	s_nop 0
	v_cndmask_b32_e32 v48, v214, v50, vcc
	s_nop 0
.LBB0_1066:
	s_add_i32 s17, s16, 8
	s_cmpk_lt_u32 s33, 0x440
	s_cselect_b64 s[46:47], -1, 0
	s_lshl_b32 s22, s17, 6
	s_mov_b64 s[12:13], -1
	s_and_b64 vcc, exec, s[46:47]
	s_cbranch_vccnz .LBB0_1068
	v_add_u32_e32 v48, s22, v213
	v_mul_hi_u32 v49, v48, s75
	v_lshrrev_b32_e32 v49, 1, v49
	v_lshl_add_u32 v50, v49, 3, v49
	v_sub_u32_e32 v48, v48, v50
	v_lshlrev_b32_e32 v50, 3, v48
	v_cmp_ne_u32_e32 vcc, 8, v48
	s_mov_b64 s[12:13], 0
	s_nop 0
	v_cndmask_b32_e32 v48, 56, v50, vcc
	s_nop 0
.LBB0_1068:
	s_andn2_b64 vcc, exec, s[12:13]
	s_cbranch_vccnz .LBB0_1070
	v_or_b32_e32 v48, s22, v184
	v_mul_hi_u32 v49, v48, s76
	v_lshrrev_b32_e32 v49, 3, v49
	v_mul_lo_u32 v50, v49, 25
	v_sub_u32_e32 v48, v48, v50
	v_lshlrev_b32_e32 v50, 3, v48
	v_cmp_ne_u32_e32 vcc, 24, v48
	v_mul_lo_u32 v49, v49, s73
	s_nop 0
	v_cndmask_b32_e32 v48, v214, v50, vcc
	s_nop 0
.LBB0_1070:
	s_add_i32 s22, s16, 16
	s_cmpk_lt_u32 s33, 0x240
	s_cselect_b64 s[48:49], -1, 0
	s_lshl_b32 s23, s22, 6
	s_mov_b64 s[12:13], -1
	s_and_b64 vcc, exec, s[48:49]
	s_cbranch_vccnz .LBB0_1072
	v_add_u32_e32 v48, s23, v213
	v_mul_hi_u32 v49, v48, s75
	v_lshrrev_b32_e32 v49, 1, v49
	v_lshl_add_u32 v50, v49, 3, v49
	v_sub_u32_e32 v48, v48, v50
	v_lshlrev_b32_e32 v50, 3, v48
	v_cmp_ne_u32_e32 vcc, 8, v48
	s_mov_b64 s[12:13], 0
	s_nop 0
	v_cndmask_b32_e32 v48, 56, v50, vcc
	s_nop 0
.LBB0_1072:
	s_andn2_b64 vcc, exec, s[12:13]
	s_cbranch_vccnz .LBB0_1074
	v_or_b32_e32 v48, s23, v184
	v_mul_hi_u32 v49, v48, s76
	v_lshrrev_b32_e32 v49, 3, v49
	v_mul_lo_u32 v50, v49, 25
	v_sub_u32_e32 v48, v48, v50
	v_lshlrev_b32_e32 v50, 3, v48
	v_cmp_ne_u32_e32 vcc, 24, v48
	v_mul_lo_u32 v49, v49, s73
	s_nop 0
	v_cndmask_b32_e32 v48, v214, v50, vcc
	s_nop 0

; #define AT_DMA(t_, slot_) do { _Pragma("unroll") for (int j = 0; j < NJ; ++j) { const int g = wid + 8 * j; if (g < NIT) { \
;         const bf16_t* src_ = (g < NKI) ? (Kp + (size_t)(t_) * 64 * ldk + goff[j]) : (VTp + (size_t)(t_) * 64 + goff[j]); \
;         __builtin_amdgcn_global_load_lds((const unsigned*)src_, (LAS unsigned*)(lds + (slot_) * BUF + g * 1024), 16, 0, 0); } } } while (0)
; #define AT_WAIT_KEEP1() do { if (full) asm volatile("s_waitcnt vmcnt(%0)" :: "n"(NJ) : "memory"); else asm volatile("s_waitcnt vmcnt(%0)" :: "n"(NJ - 1) : "memory"); } while (0)
; #define AT_WAIT_ALL() asm volatile("s_waitcnt vmcnt(0)" ::: "memory")
; template <int DQK, int QF>
; __device__ __forceinline__ void attn_unit_dma(LAS unsigned char* lds, const bf16_t* Qp, int ldq, const bf16_t* Kp, int ldk, const bf16_t* VTp, int ldvt, bf16_t* Op, int ldo, int nkt, int wave_last, const float* qgam, float qscale) {
;     ...
;     f32x4 o[QF][8];
; #pragma unroll
;     for (int qf = 0; qf < QF; ++qf)
; #pragma unroll
;         for (int mv = 0; mv < 8; ++mv) o[qf][mv] = (f32x4){0.f, 0.f, 0.f, 0.f};
;     float mrun[QF], lrun[QF];
; #pragma unroll
;     for (int qf = 0; qf < QF; ++qf) { mrun[qf] = -1e30f; lrun[qf] = 0.f; }
;     ...
;     asm volatile("s_waitcnt vmcnt(0)" ::: "memory");
;     AT_DMA(0, 0);
;     if (nkt > 1) { AT_DMA(1, 1); AT_WAIT_KEEP1(); } else AT_WAIT_ALL();
;     __builtin_amdgcn_s_barrier();
;     int slot = 0;
.LBB0_1096:
	s_waitcnt vmcnt(5)
	s_andn2_b64 vcc, exec, s[12:13]
	s_barrier
	s_cbranch_vccnz .LBB0_1060
	s_add_i32 s12, s14, s72
	s_ashr_i32 s13, s12, 31
	s_lshr_b32 s13, s13, 26
	v_add_u32_e32 v50, v54, v49
	v_mov_b32_e32 v51, v189
	s_lshl_b32 s0, s0, 2
	s_add_i32 s12, s12, s13
	v_lshl_add_u64 v[208:209], v[50:51], 1, s[36:37]
	v_add_u32_e32 v50, v56, v55
	v_mov_b32_e32 v56, 0
	s_add_i32 s0, s0, 4
	s_ashr_i32 s95, s12, 6
	v_mov_b32_e32 v201, v189
	s_lshl_b32 s97, s16, 10
	v_mov_b32_e32 v203, v189
	s_lshl_b32 s33, s17, 10
	v_mov_b32_e32 v205, v189
	s_lshl_b32 s16, s22, 10
	s_lshl_b32 s17, s23, 10
	s_lshl_b32 s22, s34, 10
	s_lshl_b32 s23, s35, 10
	v_lshl_add_u64 v[210:211], v[50:51], 1, s[36:37]
	s_mov_b32 s34, 0
	v_mov_b32_e32 v128, 0xf149f2ca
	v_lshlrev_b32_e32 v199, 1, v48
	s_mov_b64 s[66:67], s[36:37]
	s_mov_b64 s[68:69], s[28:29]
	v_mov_b32_e32 v112, 0xf149f2ca
	s_mov_b32 s35, 0
	v_mov_b32_e32 v57, v56
	v_mov_b32_e32 v58, v56
	v_mov_b32_e32 v59, v56
	v_mov_b32_e32 v60, v56
	v_mov_b32_e32 v61, v56
	v_mov_b32_e32 v62, v56
	v_mov_b32_e32 v63, v56
	v_mov_b32_e32 v64, v56
	v_mov_b32_e32 v65, v56
	v_mov_b32_e32 v66, v56
	v_mov_b32_e32 v67, v56
	v_mov_b32_e32 v68, v56
	v_mov_b32_e32 v69, v56
	v_mov_b32_e32 v70, v56
	v_mov_b32_e32 v71, v56
	v_mov_b32_e32 v48, v56
	v_mov_b32_e32 v49, v56
	v_mov_b32_e32 v50, v56
	v_mov_b32_e32 v51, v56
	v_mov_b32_e32 v108, v56
	v_mov_b32_e32 v109, v56
	v_mov_b32_e32 v110, v56
	v_mov_b32_e32 v111, v56
	v_mov_b32_e32 v104, v56
	v_mov_b32_e32 v105, v56
	v_mov_b32_e32 v106, v56
	v_mov_b32_e32 v107, v56
	v_mov_b32_e32 v88, v56
	v_mov_b32_e32 v89, v56
	v_mov_b32_e32 v90, v56
	v_mov_b32_e32 v91, v56
	v_mov_b32_e32 v84, v56
	v_mov_b32_e32 v85, v56
	v_mov_b32_e32 v86, v56
	v_mov_b32_e32 v87, v56
	v_mov_b32_e32 v92, v56
	v_mov_b32_e32 v93, v56
	v_mov_b32_e32 v94, v56
	v_mov_b32_e32 v95, v56
	v_mov_b32_e32 v100, v56
	v_mov_b32_e32 v101, v56
	v_mov_b32_e32 v102, v56
	v_mov_b32_e32 v103, v56
	v_mov_b32_e32 v96, v56
	v_mov_b32_e32 v97, v56
	v_mov_b32_e32 v98, v56
	v_mov_b32_e32 v99, v56
	v_mov_b32_e32 v72, v56
	v_mov_b32_e32 v73, v56
	v_mov_b32_e32 v74, v56
	v_mov_b32_e32 v75, v56
	v_mov_b32_e32 v76, v56
	v_mov_b32_e32 v77, v56
	v_mov_b32_e32 v78, v56
	v_mov_b32_e32 v79, v56
	v_mov_b32_e32 v80, v56
	v_mov_b32_e32 v81, v56
	v_mov_b32_e32 v82, v56
	v_mov_b32_e32 v83, v56
	v_mov_b32_e32 v52, v56
	v_mov_b32_e32 v53, v56
	v_mov_b32_e32 v54, v56
	v_mov_b32_e32 v55, v56
	v_mov_b32_e32 v206, v56
	v_mov_b32_e32 v207, v56
	s_waitcnt vmcnt(0)
	s_branch .LBB0_1099
